# GEMM K-loop: 4 of the 16 per-iteration LDS-DMA loads use scalar base + 32-bit lane offset (no 64-bit VALU address add in front of them)
# speedup vs baseline: 1.0093x; 1.0055x over previous
.LBB0_246:
	s_andn2_b64 vcc, exec, s[18:19]
	s_cbranch_vccnz .Lk_zero_skip
	s_add_u32 s44, s44, 0x80
	s_addc_u32 s45, s45, 0
	s_add_u32 s23, s46, 0x100
	s_addc_u32 s48, s47, 0
	s_mov_b32 s46, 0
	s_add_i32 s49, s46, 2
	s_add_u32 s69, s44, 0x80
	s_addc_u32 s47, s45, 0
	s_add_i32 s80, 0, 0x10000
	s_cmp_eq_u32 s90, s46
	s_cselect_b32 s47, s65, s47
	s_cselect_b32 s46, s64, s69
	s_cselect_b32 s71, s67, s48
	s_cselect_b32 s70, s66, s23
	s_add_i32 s69, 0, 0x14000
	v_add_u32_e32 v140, s80, v227
	v_add_u32_e32 v152, s69, v227
	ds_read_b128 v[128:131], v140
	ds_read_b128 v[132:135], v140 offset:1024
	ds_read_b128 v[136:139], v140 offset:2048
	ds_read_b128 v[140:143], v140 offset:3072
	ds_read_b128 v[144:147], v152
	ds_read_b128 v[148:151], v152 offset:1024
	ds_read_b128 v[174:177], v152 offset:2048
	ds_read_b128 v[178:181], v152 offset:3072
	s_add_i32 m0, s50, 0xc000
	ds_read_b128 v[182:185], v230
	ds_read_b128 v[186:189], v230 offset:1024
	ds_read_b128 v[190:193], v230 offset:2048
	ds_read_b128 v[194:197], v230 offset:3072
	ds_read_b128 v[198:201], v230 offset:4096
	ds_read_b128 v[202:205], v230 offset:5120
	ds_read_b128 v[206:209], v230 offset:6144
	ds_read_b128 v[232:235], v230 offset:7168
	global_load_lds_dwordx4 v170, s[44:45]
	s_add_i32 m0, s50, 0xe000
	s_nop 0
	global_load_lds_dwordx4 v172, s[44:45]
	s_waitcnt vmcnt(8)
	s_waitcnt lgkmcnt(0)
	s_barrier
	s_setprio 1
	s_waitcnt lgkmcnt(0)
	v_mfma_f32_16x16x32_bf16 v[16:19], v[128:131], v[182:185], 0
	v_mfma_f32_16x16x32_bf16 v[28:31], v[136:139], v[182:185], 0
	v_mfma_f32_16x16x32_bf16 v[12:15], v[128:131], v[190:193], 0
	v_mfma_f32_16x16x32_bf16 v[8:11], v[136:139], v[190:193], 0
	v_mfma_f32_16x16x32_bf16 v[124:127], v[128:131], v[198:201], 0
	v_mfma_f32_16x16x32_bf16 v[120:123], v[136:139], v[198:201], 0
	v_mfma_f32_16x16x32_bf16 v[108:111], v[128:131], v[206:209], 0
	v_mfma_f32_16x16x32_bf16 v[104:107], v[136:139], v[206:209], 0
	v_mfma_f32_16x16x32_bf16 v[16:19], v[132:135], v[186:189], v[16:19]
	v_mfma_f32_16x16x32_bf16 v[28:31], v[140:143], v[186:189], v[28:31]
	v_mfma_f32_16x16x32_bf16 v[12:15], v[132:135], v[194:197], v[12:15]
	v_mfma_f32_16x16x32_bf16 v[8:11], v[140:143], v[194:197], v[8:11]
	v_mfma_f32_16x16x32_bf16 v[124:127], v[132:135], v[202:205], v[124:127]
	v_mfma_f32_16x16x32_bf16 v[120:123], v[140:143], v[202:205], v[120:123]
	v_mfma_f32_16x16x32_bf16 v[108:111], v[132:135], v[232:235], v[108:111]
	v_mfma_f32_16x16x32_bf16 v[104:107], v[140:143], v[232:235], v[104:107]
	s_setprio 0
	s_setprio 1
	v_mfma_f32_16x16x32_bf16 v[24:27], v[144:147], v[182:185], 0
	v_mfma_f32_16x16x32_bf16 v[20:23], v[174:177], v[182:185], 0
	v_mfma_f32_16x16x32_bf16 v[4:7], v[144:147], v[190:193], 0
	v_mfma_f32_16x16x32_bf16 v[0:3], v[174:177], v[190:193], 0
	v_mfma_f32_16x16x32_bf16 v[116:119], v[144:147], v[198:201], 0
	v_mfma_f32_16x16x32_bf16 v[112:115], v[174:177], v[198:201], 0
	v_mfma_f32_16x16x32_bf16 v[100:103], v[144:147], v[206:209], 0
	v_mfma_f32_16x16x32_bf16 v[96:99], v[174:177], v[206:209], 0
	v_mfma_f32_16x16x32_bf16 v[24:27], v[148:151], v[186:189], v[24:27]
	v_mfma_f32_16x16x32_bf16 v[20:23], v[178:181], v[186:189], v[20:23]
	v_mfma_f32_16x16x32_bf16 v[4:7], v[148:151], v[194:197], v[4:7]
	v_mfma_f32_16x16x32_bf16 v[0:3], v[178:181], v[194:197], v[0:3]
	v_mfma_f32_16x16x32_bf16 v[116:119], v[148:151], v[202:205], v[116:119]
	v_mfma_f32_16x16x32_bf16 v[112:115], v[178:181], v[202:205], v[112:115]
	v_mfma_f32_16x16x32_bf16 v[100:103], v[148:151], v[232:235], v[100:103]
	v_mfma_f32_16x16x32_bf16 v[96:99], v[178:181], v[232:235], v[96:99]
	s_setprio 0
	s_barrier
	s_add_i32 s80, s80, s3
	v_lshl_add_u64 v[210:211], s[70:71], 0, v[160:161]
	s_mov_b32 m0, s80
	ds_read_b128 v[182:185], v230 offset:16384
	ds_read_b128 v[186:189], v230 offset:17408
	ds_read_b128 v[190:193], v230 offset:18432
	ds_read_b128 v[194:197], v230 offset:19456
	ds_read_b128 v[198:201], v230 offset:20480
	ds_read_b128 v[202:205], v230 offset:21504
	ds_read_b128 v[206:209], v230 offset:22528
	ds_read_b128 v[232:235], v230 offset:23552
	global_load_lds_dwordx4 v[210:211], off
	s_add_i32 m0, s80, 0x2000
	v_lshl_add_u64 v[236:237], s[70:71], 0, v[164:165]
	s_add_u32 s70, s70, s26
	s_addc_u32 s71, s71, 0
	s_add_i32 s69, s69, s3
	global_load_lds_dwordx4 v[236:237], off
	v_lshl_add_u64 v[238:239], s[70:71], 0, v[160:161]
	s_mov_b32 m0, s69
	v_lshl_add_u64 v[240:241], s[70:71], 0, v[164:165]
	global_load_lds_dwordx4 v[238:239], off
	s_add_i32 m0, s69, 0x2000
	v_lshl_add_u64 v[242:243], s[46:47], 0, v[158:159]
	global_load_lds_dwordx4 v[240:241], off
	s_mov_b32 m0, s50
	v_lshl_add_u64 v[244:245], s[46:47], 0, v[162:163]
	global_load_lds_dwordx4 v[242:243], off
	s_mov_b32 m0, s51
	s_nop 0
	global_load_lds_dwordx4 v[244:245], off
	s_waitcnt vmcnt(8)
	s_waitcnt lgkmcnt(0)
	s_barrier
	s_setprio 1
	s_waitcnt lgkmcnt(0)
	v_mfma_f32_16x16x32_bf16 v[92:95], v[128:131], v[182:185], 0
	v_mfma_f32_16x16x32_bf16 v[88:91], v[136:139], v[182:185], 0
	v_mfma_f32_16x16x32_bf16 v[76:79], v[128:131], v[190:193], 0
	v_mfma_f32_16x16x32_bf16 v[72:75], v[136:139], v[190:193], 0
	v_mfma_f32_16x16x32_bf16 v[60:63], v[128:131], v[198:201], 0
	v_mfma_f32_16x16x32_bf16 v[56:59], v[136:139], v[198:201], 0
	v_mfma_f32_16x16x32_bf16 v[44:47], v[128:131], v[206:209], 0
	v_mfma_f32_16x16x32_bf16 v[40:43], v[136:139], v[206:209], 0
	v_mfma_f32_16x16x32_bf16 v[92:95], v[132:135], v[186:189], v[92:95]
	v_mfma_f32_16x16x32_bf16 v[88:91], v[140:143], v[186:189], v[88:91]
	v_mfma_f32_16x16x32_bf16 v[76:79], v[132:135], v[194:197], v[76:79]
	v_mfma_f32_16x16x32_bf16 v[72:75], v[140:143], v[194:197], v[72:75]
	v_mfma_f32_16x16x32_bf16 v[60:63], v[132:135], v[202:205], v[60:63]
	v_mfma_f32_16x16x32_bf16 v[56:59], v[140:143], v[202:205], v[56:59]
	v_mfma_f32_16x16x32_bf16 v[44:47], v[132:135], v[232:235], v[44:47]
	v_mfma_f32_16x16x32_bf16 v[40:43], v[140:143], v[232:235], v[40:43]
	s_setprio 0
	s_setprio 1
	v_mfma_f32_16x16x32_bf16 v[84:87], v[144:147], v[182:185], 0
	v_mfma_f32_16x16x32_bf16 v[80:83], v[174:177], v[182:185], 0
	v_mfma_f32_16x16x32_bf16 v[68:71], v[144:147], v[190:193], 0
	v_mfma_f32_16x16x32_bf16 v[64:67], v[174:177], v[190:193], 0
	v_mfma_f32_16x16x32_bf16 v[52:55], v[144:147], v[198:201], 0
	v_mfma_f32_16x16x32_bf16 v[48:51], v[174:177], v[198:201], 0
	v_mfma_f32_16x16x32_bf16 v[36:39], v[144:147], v[206:209], 0
	v_mfma_f32_16x16x32_bf16 v[32:35], v[174:177], v[206:209], 0
	v_mfma_f32_16x16x32_bf16 v[84:87], v[148:151], v[186:189], v[84:87]
	v_mfma_f32_16x16x32_bf16 v[80:83], v[178:181], v[186:189], v[80:83]
	v_mfma_f32_16x16x32_bf16 v[68:71], v[148:151], v[194:197], v[68:71]
	v_mfma_f32_16x16x32_bf16 v[64:67], v[178:181], v[194:197], v[64:67]
	v_mfma_f32_16x16x32_bf16 v[52:55], v[148:151], v[202:205], v[52:55]
	v_mfma_f32_16x16x32_bf16 v[48:51], v[178:181], v[202:205], v[48:51]
	v_mfma_f32_16x16x32_bf16 v[36:39], v[148:151], v[232:235], v[36:39]
	v_mfma_f32_16x16x32_bf16 v[32:35], v[178:181], v[232:235], v[32:35]
	s_setprio 0
	s_barrier
	s_add_i32 s69, 0, 0x18000
	s_add_i32 s70, 0, 0x1c000
	v_add_u32_e32 v140, s69, v227
	v_add_u32_e32 v152, s70, v227
	ds_read_b128 v[128:131], v140
	ds_read_b128 v[132:135], v140 offset:1024
	ds_read_b128 v[136:139], v140 offset:2048
	ds_read_b128 v[140:143], v140 offset:3072
	ds_read_b128 v[144:147], v152
	ds_read_b128 v[148:151], v152 offset:1024
	ds_read_b128 v[174:177], v152 offset:2048
	ds_read_b128 v[178:181], v152 offset:3072
	s_add_u32 s46, s46, s26
	s_addc_u32 s47, s47, 0
	s_mov_b32 m0, s8
	ds_read_b128 v[182:185], v230 offset:32768
	ds_read_b128 v[186:189], v230 offset:33792
	ds_read_b128 v[190:193], v230 offset:34816
	ds_read_b128 v[194:197], v230 offset:35840
	ds_read_b128 v[198:201], v230 offset:36864
	ds_read_b128 v[202:205], v230 offset:37888
	ds_read_b128 v[206:209], v230 offset:38912
	ds_read_b128 v[232:235], v230 offset:39936
	global_load_lds_dwordx4 v158, s[46:47]
	s_mov_b32 m0, s9
	s_nop 0
	global_load_lds_dwordx4 v162, s[46:47]
	s_waitcnt vmcnt(8)
	s_waitcnt lgkmcnt(0)
	s_barrier
	s_setprio 1
	s_waitcnt lgkmcnt(0)
	v_mfma_f32_16x16x32_bf16 v[16:19], v[128:131], v[182:185], v[16:19]
	v_mfma_f32_16x16x32_bf16 v[28:31], v[136:139], v[182:185], v[28:31]
	v_mfma_f32_16x16x32_bf16 v[12:15], v[128:131], v[190:193], v[12:15]
	v_mfma_f32_16x16x32_bf16 v[8:11], v[136:139], v[190:193], v[8:11]
	v_mfma_f32_16x16x32_bf16 v[124:127], v[128:131], v[198:201], v[124:127]
	v_mfma_f32_16x16x32_bf16 v[120:123], v[136:139], v[198:201], v[120:123]
	v_mfma_f32_16x16x32_bf16 v[108:111], v[128:131], v[206:209], v[108:111]
	v_mfma_f32_16x16x32_bf16 v[104:107], v[136:139], v[206:209], v[104:107]
	v_mfma_f32_16x16x32_bf16 v[16:19], v[132:135], v[186:189], v[16:19]
	v_mfma_f32_16x16x32_bf16 v[28:31], v[140:143], v[186:189], v[28:31]
	v_mfma_f32_16x16x32_bf16 v[12:15], v[132:135], v[194:197], v[12:15]
	v_mfma_f32_16x16x32_bf16 v[8:11], v[140:143], v[194:197], v[8:11]
	v_mfma_f32_16x16x32_bf16 v[124:127], v[132:135], v[202:205], v[124:127]
	v_mfma_f32_16x16x32_bf16 v[120:123], v[140:143], v[202:205], v[120:123]
	v_mfma_f32_16x16x32_bf16 v[108:111], v[132:135], v[232:235], v[108:111]
	v_mfma_f32_16x16x32_bf16 v[104:107], v[140:143], v[232:235], v[104:107]
	s_setprio 0
	s_setprio 1
	v_mfma_f32_16x16x32_bf16 v[24:27], v[144:147], v[182:185], v[24:27]
	v_mfma_f32_16x16x32_bf16 v[20:23], v[174:177], v[182:185], v[20:23]
	v_mfma_f32_16x16x32_bf16 v[4:7], v[144:147], v[190:193], v[4:7]
	v_mfma_f32_16x16x32_bf16 v[0:3], v[174:177], v[190:193], v[0:3]
	v_mfma_f32_16x16x32_bf16 v[116:119], v[144:147], v[198:201], v[116:119]
	v_mfma_f32_16x16x32_bf16 v[112:115], v[174:177], v[198:201], v[112:115]
	v_mfma_f32_16x16x32_bf16 v[100:103], v[144:147], v[206:209], v[100:103]
	v_mfma_f32_16x16x32_bf16 v[96:99], v[174:177], v[206:209], v[96:99]
	v_mfma_f32_16x16x32_bf16 v[24:27], v[148:151], v[186:189], v[24:27]
	v_mfma_f32_16x16x32_bf16 v[20:23], v[178:181], v[186:189], v[20:23]
	v_mfma_f32_16x16x32_bf16 v[4:7], v[148:151], v[194:197], v[4:7]
	v_mfma_f32_16x16x32_bf16 v[0:3], v[178:181], v[194:197], v[0:3]
	v_mfma_f32_16x16x32_bf16 v[116:119], v[148:151], v[202:205], v[116:119]
	v_mfma_f32_16x16x32_bf16 v[112:115], v[178:181], v[202:205], v[112:115]
	v_mfma_f32_16x16x32_bf16 v[100:103], v[148:151], v[232:235], v[100:103]
	v_mfma_f32_16x16x32_bf16 v[96:99], v[178:181], v[232:235], v[96:99]
	s_setprio 0
	s_barrier
	s_add_i32 s46, s69, s3
	v_lshl_add_u64 v[210:211], v[210:211], 0, s[6:7]
	s_mov_b32 m0, s46
	ds_read_b128 v[182:185], v230 offset:49152
	ds_read_b128 v[186:189], v230 offset:50176
	ds_read_b128 v[190:193], v230 offset:51200
	ds_read_b128 v[194:197], v230 offset:52224
	ds_read_b128 v[198:201], v230 offset:53248
	ds_read_b128 v[202:205], v230 offset:54272
	ds_read_b128 v[206:209], v230 offset:55296
	ds_read_b128 v[232:235], v230 offset:56320
	global_load_lds_dwordx4 v[210:211], off
	v_lshl_add_u64 v[210:211], v[236:237], 0, s[6:7]
	s_add_i32 m0, s46, 0x2000
	s_add_i32 s46, s70, s3
	global_load_lds_dwordx4 v[210:211], off
	v_lshl_add_u64 v[210:211], v[238:239], 0, s[6:7]
	s_mov_b32 m0, s46
	s_nop 0
	global_load_lds_dwordx4 v[210:211], off
	v_lshl_add_u64 v[210:211], v[240:241], 0, s[6:7]
	s_add_i32 m0, s46, 0x2000
	s_nop 0
	global_load_lds_dwordx4 v[210:211], off
	v_lshl_add_u64 v[210:211], v[242:243], 0, s[6:7]
	s_mov_b32 m0, s30
	s_nop 0
	global_load_lds_dwordx4 v[210:211], off
	v_lshl_add_u64 v[210:211], v[244:245], 0, s[6:7]
	s_mov_b32 m0, s31
	s_nop 0
	global_load_lds_dwordx4 v[210:211], off
	s_waitcnt vmcnt(8)
	s_waitcnt lgkmcnt(0)
	s_barrier
	s_setprio 1
	s_waitcnt lgkmcnt(0)
	v_mfma_f32_16x16x32_bf16 v[92:95], v[128:131], v[182:185], v[92:95]
	v_mfma_f32_16x16x32_bf16 v[88:91], v[136:139], v[182:185], v[88:91]
	v_mfma_f32_16x16x32_bf16 v[76:79], v[128:131], v[190:193], v[76:79]
	v_mfma_f32_16x16x32_bf16 v[72:75], v[136:139], v[190:193], v[72:75]
	v_mfma_f32_16x16x32_bf16 v[60:63], v[128:131], v[198:201], v[60:63]
	v_mfma_f32_16x16x32_bf16 v[56:59], v[136:139], v[198:201], v[56:59]
	v_mfma_f32_16x16x32_bf16 v[44:47], v[128:131], v[206:209], v[44:47]
	v_mfma_f32_16x16x32_bf16 v[40:43], v[136:139], v[206:209], v[40:43]
	v_mfma_f32_16x16x32_bf16 v[92:95], v[132:135], v[186:189], v[92:95]
	v_mfma_f32_16x16x32_bf16 v[88:91], v[140:143], v[186:189], v[88:91]
	v_mfma_f32_16x16x32_bf16 v[76:79], v[132:135], v[194:197], v[76:79]
	v_mfma_f32_16x16x32_bf16 v[72:75], v[140:143], v[194:197], v[72:75]
	v_mfma_f32_16x16x32_bf16 v[60:63], v[132:135], v[202:205], v[60:63]
	v_mfma_f32_16x16x32_bf16 v[56:59], v[140:143], v[202:205], v[56:59]
	v_mfma_f32_16x16x32_bf16 v[44:47], v[132:135], v[232:235], v[44:47]
	v_mfma_f32_16x16x32_bf16 v[40:43], v[140:143], v[232:235], v[40:43]
	s_setprio 0
	s_setprio 1
	v_mfma_f32_16x16x32_bf16 v[84:87], v[144:147], v[182:185], v[84:87]
	v_mfma_f32_16x16x32_bf16 v[80:83], v[174:177], v[182:185], v[80:83]
	v_mfma_f32_16x16x32_bf16 v[68:71], v[144:147], v[190:193], v[68:71]
	v_mfma_f32_16x16x32_bf16 v[64:67], v[174:177], v[190:193], v[64:67]
	v_mfma_f32_16x16x32_bf16 v[52:55], v[144:147], v[198:201], v[52:55]
	v_mfma_f32_16x16x32_bf16 v[48:51], v[174:177], v[198:201], v[48:51]
	v_mfma_f32_16x16x32_bf16 v[36:39], v[144:147], v[206:209], v[36:39]
	v_mfma_f32_16x16x32_bf16 v[32:35], v[174:177], v[206:209], v[32:35]
	v_mfma_f32_16x16x32_bf16 v[84:87], v[148:151], v[186:189], v[84:87]
	v_mfma_f32_16x16x32_bf16 v[80:83], v[178:181], v[186:189], v[80:83]
	v_mfma_f32_16x16x32_bf16 v[68:71], v[148:151], v[194:197], v[68:71]
	v_mfma_f32_16x16x32_bf16 v[64:67], v[178:181], v[194:197], v[64:67]
	v_mfma_f32_16x16x32_bf16 v[52:55], v[148:151], v[202:205], v[52:55]
	v_mfma_f32_16x16x32_bf16 v[48:51], v[178:181], v[202:205], v[48:51]
	v_mfma_f32_16x16x32_bf16 v[36:39], v[148:151], v[232:235], v[36:39]
	v_mfma_f32_16x16x32_bf16 v[32:35], v[178:181], v[232:235], v[32:35]
	s_setprio 0
	s_barrier
	s_add_u32 s44, s44, 0x100
	s_addc_u32 s45, s45, 0
	s_add_u32 s23, s23, 0x100
	s_addc_u32 s48, s48, 0
	s_cmp_ge_u32 s49, s88
	s_mov_b32 s46, s49
	s_cbranch_scc1 .LBB0_249
.LBB0_248:
	s_add_i32 s49, s46, 2
	s_add_u32 s69, s44, 0x80
	s_addc_u32 s47, s45, 0
	s_add_i32 s80, 0, 0x10000
	s_cmp_eq_u32 s90, s46
	s_cselect_b32 s47, s65, s47
	s_cselect_b32 s46, s64, s69
	s_cselect_b32 s71, s67, s48
	s_cselect_b32 s70, s66, s23
	s_add_i32 s69, 0, 0x14000
	v_add_u32_e32 v140, s80, v227
	v_add_u32_e32 v152, s69, v227
	ds_read_b128 v[128:131], v140
	ds_read_b128 v[132:135], v140 offset:1024
	ds_read_b128 v[136:139], v140 offset:2048
	ds_read_b128 v[140:143], v140 offset:3072
	ds_read_b128 v[144:147], v152
	ds_read_b128 v[148:151], v152 offset:1024
	ds_read_b128 v[174:177], v152 offset:2048
	ds_read_b128 v[178:181], v152 offset:3072
	s_add_i32 m0, s50, 0xc000
	ds_read_b128 v[182:185], v230
	ds_read_b128 v[186:189], v230 offset:1024
	ds_read_b128 v[190:193], v230 offset:2048
	ds_read_b128 v[194:197], v230 offset:3072
	ds_read_b128 v[198:201], v230 offset:4096
	ds_read_b128 v[202:205], v230 offset:5120
	ds_read_b128 v[206:209], v230 offset:6144
	ds_read_b128 v[232:235], v230 offset:7168
	global_load_lds_dwordx4 v170, s[44:45]
	s_add_i32 m0, s50, 0xe000
	s_nop 0
	global_load_lds_dwordx4 v172, s[44:45]
	s_waitcnt vmcnt(8)
	s_waitcnt lgkmcnt(0)
	s_barrier
	s_setprio 1
	s_waitcnt lgkmcnt(0)
	v_mfma_f32_16x16x32_bf16 v[16:19], v[128:131], v[182:185], v[16:19]
	v_mfma_f32_16x16x32_bf16 v[28:31], v[136:139], v[182:185], v[28:31]
	v_mfma_f32_16x16x32_bf16 v[12:15], v[128:131], v[190:193], v[12:15]
	v_mfma_f32_16x16x32_bf16 v[8:11], v[136:139], v[190:193], v[8:11]
	v_mfma_f32_16x16x32_bf16 v[124:127], v[128:131], v[198:201], v[124:127]
	v_mfma_f32_16x16x32_bf16 v[120:123], v[136:139], v[198:201], v[120:123]
	v_mfma_f32_16x16x32_bf16 v[108:111], v[128:131], v[206:209], v[108:111]
	v_mfma_f32_16x16x32_bf16 v[104:107], v[136:139], v[206:209], v[104:107]
	v_mfma_f32_16x16x32_bf16 v[16:19], v[132:135], v[186:189], v[16:19]
	v_mfma_f32_16x16x32_bf16 v[28:31], v[140:143], v[186:189], v[28:31]
	v_mfma_f32_16x16x32_bf16 v[12:15], v[132:135], v[194:197], v[12:15]
	v_mfma_f32_16x16x32_bf16 v[8:11], v[140:143], v[194:197], v[8:11]
	v_mfma_f32_16x16x32_bf16 v[124:127], v[132:135], v[202:205], v[124:127]
	v_mfma_f32_16x16x32_bf16 v[120:123], v[140:143], v[202:205], v[120:123]
	v_mfma_f32_16x16x32_bf16 v[108:111], v[132:135], v[232:235], v[108:111]
	v_mfma_f32_16x16x32_bf16 v[104:107], v[140:143], v[232:235], v[104:107]
	s_setprio 0
	s_setprio 1
	v_mfma_f32_16x16x32_bf16 v[24:27], v[144:147], v[182:185], v[24:27]
	v_mfma_f32_16x16x32_bf16 v[20:23], v[174:177], v[182:185], v[20:23]
	v_mfma_f32_16x16x32_bf16 v[4:7], v[144:147], v[190:193], v[4:7]
	v_mfma_f32_16x16x32_bf16 v[0:3], v[174:177], v[190:193], v[0:3]
	v_mfma_f32_16x16x32_bf16 v[116:119], v[144:147], v[198:201], v[116:119]
	v_mfma_f32_16x16x32_bf16 v[112:115], v[174:177], v[198:201], v[112:115]
	v_mfma_f32_16x16x32_bf16 v[100:103], v[144:147], v[206:209], v[100:103]
	v_mfma_f32_16x16x32_bf16 v[96:99], v[174:177], v[206:209], v[96:99]
	v_mfma_f32_16x16x32_bf16 v[24:27], v[148:151], v[186:189], v[24:27]
	v_mfma_f32_16x16x32_bf16 v[20:23], v[178:181], v[186:189], v[20:23]
	v_mfma_f32_16x16x32_bf16 v[4:7], v[148:151], v[194:197], v[4:7]
	v_mfma_f32_16x16x32_bf16 v[0:3], v[178:181], v[194:197], v[0:3]
	v_mfma_f32_16x16x32_bf16 v[116:119], v[148:151], v[202:205], v[116:119]
	v_mfma_f32_16x16x32_bf16 v[112:115], v[178:181], v[202:205], v[112:115]
	v_mfma_f32_16x16x32_bf16 v[100:103], v[148:151], v[232:235], v[100:103]
	v_mfma_f32_16x16x32_bf16 v[96:99], v[178:181], v[232:235], v[96:99]
	s_setprio 0
	s_barrier
	s_add_i32 s80, s80, s3
	v_lshl_add_u64 v[210:211], s[70:71], 0, v[160:161]
	s_mov_b32 m0, s80
	ds_read_b128 v[182:185], v230 offset:16384
	ds_read_b128 v[186:189], v230 offset:17408
	ds_read_b128 v[190:193], v230 offset:18432
	ds_read_b128 v[194:197], v230 offset:19456
	ds_read_b128 v[198:201], v230 offset:20480
	ds_read_b128 v[202:205], v230 offset:21504
	ds_read_b128 v[206:209], v230 offset:22528
	ds_read_b128 v[232:235], v230 offset:23552
	global_load_lds_dwordx4 v[210:211], off
	s_add_i32 m0, s80, 0x2000
	v_lshl_add_u64 v[236:237], s[70:71], 0, v[164:165]
	s_add_u32 s70, s70, s26
	s_addc_u32 s71, s71, 0
	s_add_i32 s69, s69, s3
	global_load_lds_dwordx4 v[236:237], off
	v_lshl_add_u64 v[238:239], s[70:71], 0, v[160:161]
	s_mov_b32 m0, s69
	v_lshl_add_u64 v[240:241], s[70:71], 0, v[164:165]
	global_load_lds_dwordx4 v[238:239], off
	s_add_i32 m0, s69, 0x2000
	v_lshl_add_u64 v[242:243], s[46:47], 0, v[158:159]
	global_load_lds_dwordx4 v[240:241], off
	s_mov_b32 m0, s50
	v_lshl_add_u64 v[244:245], s[46:47], 0, v[162:163]
	global_load_lds_dwordx4 v[242:243], off
	s_mov_b32 m0, s51
	s_nop 0
	global_load_lds_dwordx4 v[244:245], off
	s_waitcnt vmcnt(8)
	s_waitcnt lgkmcnt(0)
	s_barrier
	s_setprio 1
	s_waitcnt lgkmcnt(0)
	v_mfma_f32_16x16x32_bf16 v[92:95], v[128:131], v[182:185], v[92:95]
	v_mfma_f32_16x16x32_bf16 v[88:91], v[136:139], v[182:185], v[88:91]
	v_mfma_f32_16x16x32_bf16 v[76:79], v[128:131], v[190:193], v[76:79]
	v_mfma_f32_16x16x32_bf16 v[72:75], v[136:139], v[190:193], v[72:75]
	v_mfma_f32_16x16x32_bf16 v[60:63], v[128:131], v[198:201], v[60:63]
	v_mfma_f32_16x16x32_bf16 v[56:59], v[136:139], v[198:201], v[56:59]
	v_mfma_f32_16x16x32_bf16 v[44:47], v[128:131], v[206:209], v[44:47]
	v_mfma_f32_16x16x32_bf16 v[40:43], v[136:139], v[206:209], v[40:43]
	v_mfma_f32_16x16x32_bf16 v[92:95], v[132:135], v[186:189], v[92:95]
	v_mfma_f32_16x16x32_bf16 v[88:91], v[140:143], v[186:189], v[88:91]
	v_mfma_f32_16x16x32_bf16 v[76:79], v[132:135], v[194:197], v[76:79]
	v_mfma_f32_16x16x32_bf16 v[72:75], v[140:143], v[194:197], v[72:75]
	v_mfma_f32_16x16x32_bf16 v[60:63], v[132:135], v[202:205], v[60:63]
	v_mfma_f32_16x16x32_bf16 v[56:59], v[140:143], v[202:205], v[56:59]
	v_mfma_f32_16x16x32_bf16 v[44:47], v[132:135], v[232:235], v[44:47]
	v_mfma_f32_16x16x32_bf16 v[40:43], v[140:143], v[232:235], v[40:43]
	s_setprio 0
	s_setprio 1
	v_mfma_f32_16x16x32_bf16 v[84:87], v[144:147], v[182:185], v[84:87]
	v_mfma_f32_16x16x32_bf16 v[80:83], v[174:177], v[182:185], v[80:83]
	v_mfma_f32_16x16x32_bf16 v[68:71], v[144:147], v[190:193], v[68:71]
	v_mfma_f32_16x16x32_bf16 v[64:67], v[174:177], v[190:193], v[64:67]
	v_mfma_f32_16x16x32_bf16 v[52:55], v[144:147], v[198:201], v[52:55]
	v_mfma_f32_16x16x32_bf16 v[48:51], v[174:177], v[198:201], v[48:51]
	v_mfma_f32_16x16x32_bf16 v[36:39], v[144:147], v[206:209], v[36:39]
	v_mfma_f32_16x16x32_bf16 v[32:35], v[174:177], v[206:209], v[32:35]
	v_mfma_f32_16x16x32_bf16 v[84:87], v[148:151], v[186:189], v[84:87]
	v_mfma_f32_16x16x32_bf16 v[80:83], v[178:181], v[186:189], v[80:83]
	v_mfma_f32_16x16x32_bf16 v[68:71], v[148:151], v[194:197], v[68:71]
	v_mfma_f32_16x16x32_bf16 v[64:67], v[178:181], v[194:197], v[64:67]
	v_mfma_f32_16x16x32_bf16 v[52:55], v[148:151], v[202:205], v[52:55]
	v_mfma_f32_16x16x32_bf16 v[48:51], v[178:181], v[202:205], v[48:51]
	v_mfma_f32_16x16x32_bf16 v[36:39], v[148:151], v[232:235], v[36:39]
	v_mfma_f32_16x16x32_bf16 v[32:35], v[178:181], v[232:235], v[32:35]
	s_setprio 0
	s_barrier
	s_add_i32 s69, 0, 0x18000
	s_add_i32 s70, 0, 0x1c000
	v_add_u32_e32 v140, s69, v227
	v_add_u32_e32 v152, s70, v227
	ds_read_b128 v[128:131], v140
	ds_read_b128 v[132:135], v140 offset:1024
	ds_read_b128 v[136:139], v140 offset:2048
	ds_read_b128 v[140:143], v140 offset:3072
	ds_read_b128 v[144:147], v152
	ds_read_b128 v[148:151], v152 offset:1024
	ds_read_b128 v[174:177], v152 offset:2048
	ds_read_b128 v[178:181], v152 offset:3072
	s_add_u32 s46, s46, s26
	s_addc_u32 s47, s47, 0
	s_mov_b32 m0, s8
	ds_read_b128 v[182:185], v230 offset:32768
	ds_read_b128 v[186:189], v230 offset:33792
	ds_read_b128 v[190:193], v230 offset:34816
	ds_read_b128 v[194:197], v230 offset:35840
	ds_read_b128 v[198:201], v230 offset:36864
	ds_read_b128 v[202:205], v230 offset:37888
	ds_read_b128 v[206:209], v230 offset:38912
	ds_read_b128 v[232:235], v230 offset:39936
	global_load_lds_dwordx4 v158, s[46:47]
	s_mov_b32 m0, s9
	s_nop 0
	global_load_lds_dwordx4 v162, s[46:47]
	s_waitcnt vmcnt(8)
	s_waitcnt lgkmcnt(0)
	s_barrier
	s_setprio 1
	s_waitcnt lgkmcnt(0)
	v_mfma_f32_16x16x32_bf16 v[16:19], v[128:131], v[182:185], v[16:19]
	v_mfma_f32_16x16x32_bf16 v[28:31], v[136:139], v[182:185], v[28:31]
	v_mfma_f32_16x16x32_bf16 v[12:15], v[128:131], v[190:193], v[12:15]
	v_mfma_f32_16x16x32_bf16 v[8:11], v[136:139], v[190:193], v[8:11]
	v_mfma_f32_16x16x32_bf16 v[124:127], v[128:131], v[198:201], v[124:127]
	v_mfma_f32_16x16x32_bf16 v[120:123], v[136:139], v[198:201], v[120:123]
	v_mfma_f32_16x16x32_bf16 v[108:111], v[128:131], v[206:209], v[108:111]
	v_mfma_f32_16x16x32_bf16 v[104:107], v[136:139], v[206:209], v[104:107]
	v_mfma_f32_16x16x32_bf16 v[16:19], v[132:135], v[186:189], v[16:19]
	v_mfma_f32_16x16x32_bf16 v[28:31], v[140:143], v[186:189], v[28:31]
	v_mfma_f32_16x16x32_bf16 v[12:15], v[132:135], v[194:197], v[12:15]
	v_mfma_f32_16x16x32_bf16 v[8:11], v[140:143], v[194:197], v[8:11]
	v_mfma_f32_16x16x32_bf16 v[124:127], v[132:135], v[202:205], v[124:127]
	v_mfma_f32_16x16x32_bf16 v[120:123], v[140:143], v[202:205], v[120:123]
	v_mfma_f32_16x16x32_bf16 v[108:111], v[132:135], v[232:235], v[108:111]
	v_mfma_f32_16x16x32_bf16 v[104:107], v[140:143], v[232:235], v[104:107]
	s_setprio 0
	s_setprio 1
	v_mfma_f32_16x16x32_bf16 v[24:27], v[144:147], v[182:185], v[24:27]
	v_mfma_f32_16x16x32_bf16 v[20:23], v[174:177], v[182:185], v[20:23]
	v_mfma_f32_16x16x32_bf16 v[4:7], v[144:147], v[190:193], v[4:7]
	v_mfma_f32_16x16x32_bf16 v[0:3], v[174:177], v[190:193], v[0:3]
	v_mfma_f32_16x16x32_bf16 v[116:119], v[144:147], v[198:201], v[116:119]
	v_mfma_f32_16x16x32_bf16 v[112:115], v[174:177], v[198:201], v[112:115]
	v_mfma_f32_16x16x32_bf16 v[100:103], v[144:147], v[206:209], v[100:103]
	v_mfma_f32_16x16x32_bf16 v[96:99], v[174:177], v[206:209], v[96:99]
	v_mfma_f32_16x16x32_bf16 v[24:27], v[148:151], v[186:189], v[24:27]
	v_mfma_f32_16x16x32_bf16 v[20:23], v[178:181], v[186:189], v[20:23]
	v_mfma_f32_16x16x32_bf16 v[4:7], v[148:151], v[194:197], v[4:7]
	v_mfma_f32_16x16x32_bf16 v[0:3], v[178:181], v[194:197], v[0:3]
	v_mfma_f32_16x16x32_bf16 v[116:119], v[148:151], v[202:205], v[116:119]
	v_mfma_f32_16x16x32_bf16 v[112:115], v[178:181], v[202:205], v[112:115]
	v_mfma_f32_16x16x32_bf16 v[100:103], v[148:151], v[232:235], v[100:103]
	v_mfma_f32_16x16x32_bf16 v[96:99], v[178:181], v[232:235], v[96:99]
	s_setprio 0
	s_barrier
	s_add_i32 s46, s69, s3
	v_lshl_add_u64 v[210:211], v[210:211], 0, s[6:7]
	s_mov_b32 m0, s46
	ds_read_b128 v[182:185], v230 offset:49152
	ds_read_b128 v[186:189], v230 offset:50176
	ds_read_b128 v[190:193], v230 offset:51200
	ds_read_b128 v[194:197], v230 offset:52224
	ds_read_b128 v[198:201], v230 offset:53248
	ds_read_b128 v[202:205], v230 offset:54272
	ds_read_b128 v[206:209], v230 offset:55296
	ds_read_b128 v[232:235], v230 offset:56320
	global_load_lds_dwordx4 v[210:211], off
	v_lshl_add_u64 v[210:211], v[236:237], 0, s[6:7]
	s_add_i32 m0, s46, 0x2000
	s_add_i32 s46, s70, s3
	global_load_lds_dwordx4 v[210:211], off
	v_lshl_add_u64 v[210:211], v[238:239], 0, s[6:7]
	s_mov_b32 m0, s46
	s_nop 0
	global_load_lds_dwordx4 v[210:211], off
	v_lshl_add_u64 v[210:211], v[240:241], 0, s[6:7]
	s_add_i32 m0, s46, 0x2000
	s_nop 0
	global_load_lds_dwordx4 v[210:211], off
	v_lshl_add_u64 v[210:211], v[242:243], 0, s[6:7]
	s_mov_b32 m0, s30
	s_nop 0
	global_load_lds_dwordx4 v[210:211], off
	v_lshl_add_u64 v[210:211], v[244:245], 0, s[6:7]
	s_mov_b32 m0, s31
	s_nop 0
	global_load_lds_dwordx4 v[210:211], off
	s_waitcnt vmcnt(8)
	s_waitcnt lgkmcnt(0)
	s_barrier
	s_setprio 1
	s_waitcnt lgkmcnt(0)
	v_mfma_f32_16x16x32_bf16 v[92:95], v[128:131], v[182:185], v[92:95]
	v_mfma_f32_16x16x32_bf16 v[88:91], v[136:139], v[182:185], v[88:91]
	v_mfma_f32_16x16x32_bf16 v[76:79], v[128:131], v[190:193], v[76:79]
	v_mfma_f32_16x16x32_bf16 v[72:75], v[136:139], v[190:193], v[72:75]
	v_mfma_f32_16x16x32_bf16 v[60:63], v[128:131], v[198:201], v[60:63]
	v_mfma_f32_16x16x32_bf16 v[56:59], v[136:139], v[198:201], v[56:59]
	v_mfma_f32_16x16x32_bf16 v[44:47], v[128:131], v[206:209], v[44:47]
	v_mfma_f32_16x16x32_bf16 v[40:43], v[136:139], v[206:209], v[40:43]
	v_mfma_f32_16x16x32_bf16 v[92:95], v[132:135], v[186:189], v[92:95]
	v_mfma_f32_16x16x32_bf16 v[88:91], v[140:143], v[186:189], v[88:91]
	v_mfma_f32_16x16x32_bf16 v[76:79], v[132:135], v[194:197], v[76:79]
	v_mfma_f32_16x16x32_bf16 v[72:75], v[140:143], v[194:197], v[72:75]
	v_mfma_f32_16x16x32_bf16 v[60:63], v[132:135], v[202:205], v[60:63]
	v_mfma_f32_16x16x32_bf16 v[56:59], v[140:143], v[202:205], v[56:59]
	v_mfma_f32_16x16x32_bf16 v[44:47], v[132:135], v[232:235], v[44:47]
	v_mfma_f32_16x16x32_bf16 v[40:43], v[140:143], v[232:235], v[40:43]
	s_setprio 0
	s_setprio 1
	v_mfma_f32_16x16x32_bf16 v[84:87], v[144:147], v[182:185], v[84:87]
	v_mfma_f32_16x16x32_bf16 v[80:83], v[174:177], v[182:185], v[80:83]
	v_mfma_f32_16x16x32_bf16 v[68:71], v[144:147], v[190:193], v[68:71]
	v_mfma_f32_16x16x32_bf16 v[64:67], v[174:177], v[190:193], v[64:67]
	v_mfma_f32_16x16x32_bf16 v[52:55], v[144:147], v[198:201], v[52:55]
	v_mfma_f32_16x16x32_bf16 v[48:51], v[174:177], v[198:201], v[48:51]
	v_mfma_f32_16x16x32_bf16 v[36:39], v[144:147], v[206:209], v[36:39]
	v_mfma_f32_16x16x32_bf16 v[32:35], v[174:177], v[206:209], v[32:35]
	v_mfma_f32_16x16x32_bf16 v[84:87], v[148:151], v[186:189], v[84:87]
	v_mfma_f32_16x16x32_bf16 v[80:83], v[178:181], v[186:189], v[80:83]
	v_mfma_f32_16x16x32_bf16 v[68:71], v[148:151], v[194:197], v[68:71]
	v_mfma_f32_16x16x32_bf16 v[64:67], v[178:181], v[194:197], v[64:67]
	v_mfma_f32_16x16x32_bf16 v[52:55], v[148:151], v[202:205], v[52:55]
	v_mfma_f32_16x16x32_bf16 v[48:51], v[178:181], v[202:205], v[48:51]
	v_mfma_f32_16x16x32_bf16 v[36:39], v[148:151], v[232:235], v[36:39]
	v_mfma_f32_16x16x32_bf16 v[32:35], v[178:181], v[232:235], v[32:35]
	s_setprio 0
	s_barrier
	s_add_u32 s44, s44, 0x100
	s_addc_u32 s45, s45, 0
	s_add_u32 s23, s23, 0x100
	s_addc_u32 s48, s48, 0
	s_cmp_ge_u32 s49, s88
	s_mov_b32 s46, s49
	s_cbranch_scc0 .LBB0_248
